# combo + in-proj tile store loops (phase A and B) rewritten: 16 LDS reads in flight, SGPR-stepped base, ~60 instrs instead of ~340
# speedup vs baseline: 1.0129x; 1.0129x over previous
; template <int NTW>
; DI void inproj_tile(const Params& p, int l, int mt, int ntile, char* lds) {
;     ...
; #pragma unroll 4
;   for (int i = 0; i < NCOLS / 16; ++i) {
;     const int c = tid + 256 * i, tl = c / (NCOLS / 8), ch = c % (NCOLS / 8);
;     const u32x4 v = *(const u32x4*)(lds + tl * RS + ch * 16);
;     *(u32x4*)(proj + ((size_t)mt * 128 + tl) * NP + ntile * NCOLS + ch * 8) = v;
;   }
.LBB0_166:
	v_lshrrev_b32_e32 v128, 5, v181
	v_and_b32_e32 v129, 31, v181
	v_lshlrev_b32_e32 v129, 4, v129
	v_mad_u32_u24 v130, v128, s73, v129
	v_mad_u32_u24 v131, v128, s33, v129
	s_mul_i32 s4, s80, s33
	s_add_u32 s4, s0, s4
	s_addc_u32 s5, s1, 0
	ds_read_b128 v[0:3], v130
	ds_read_b128 v[4:7], v130 offset:4224
	ds_read_b128 v[8:11], v130 offset:8448
	ds_read_b128 v[12:15], v130 offset:12672
	ds_read_b128 v[16:19], v130 offset:16896
	ds_read_b128 v[20:23], v130 offset:21120
	ds_read_b128 v[24:27], v130 offset:25344
	ds_read_b128 v[28:31], v130 offset:29568
	ds_read_b128 v[32:35], v130 offset:33792
	ds_read_b128 v[36:39], v130 offset:38016
	ds_read_b128 v[40:43], v130 offset:42240
	ds_read_b128 v[44:47], v130 offset:46464
	ds_read_b128 v[48:51], v130 offset:50688
	ds_read_b128 v[52:55], v130 offset:54912
	ds_read_b128 v[56:59], v130 offset:59136
	ds_read_b128 v[60:63], v130 offset:63360
	s_waitcnt lgkmcnt(15)
	global_store_dwordx4 v131, v[0:3], s[4:5]
	s_add_u32 s4, s4, 0xd000
	s_addc_u32 s5, s5, 0
	s_waitcnt lgkmcnt(14)
	global_store_dwordx4 v131, v[4:7], s[4:5]
	s_add_u32 s4, s4, 0xd000
	s_addc_u32 s5, s5, 0
	s_waitcnt lgkmcnt(13)
	global_store_dwordx4 v131, v[8:11], s[4:5]
	s_add_u32 s4, s4, 0xd000
	s_addc_u32 s5, s5, 0
	s_waitcnt lgkmcnt(12)
	global_store_dwordx4 v131, v[12:15], s[4:5]
	s_add_u32 s4, s4, 0xd000
	s_addc_u32 s5, s5, 0
	s_waitcnt lgkmcnt(11)
	global_store_dwordx4 v131, v[16:19], s[4:5]
	s_add_u32 s4, s4, 0xd000
	s_addc_u32 s5, s5, 0
	s_waitcnt lgkmcnt(10)
	global_store_dwordx4 v131, v[20:23], s[4:5]
	s_add_u32 s4, s4, 0xd000
	s_addc_u32 s5, s5, 0
	s_waitcnt lgkmcnt(9)
	global_store_dwordx4 v131, v[24:27], s[4:5]
	s_add_u32 s4, s4, 0xd000
	s_addc_u32 s5, s5, 0
	s_waitcnt lgkmcnt(8)
	global_store_dwordx4 v131, v[28:31], s[4:5]
	s_add_u32 s4, s4, 0xd000
	s_addc_u32 s5, s5, 0
	s_waitcnt lgkmcnt(7)
	global_store_dwordx4 v131, v[32:35], s[4:5]
	s_add_u32 s4, s4, 0xd000
	s_addc_u32 s5, s5, 0
	s_waitcnt lgkmcnt(6)
	global_store_dwordx4 v131, v[36:39], s[4:5]
	s_add_u32 s4, s4, 0xd000
	s_addc_u32 s5, s5, 0
	s_waitcnt lgkmcnt(5)
	global_store_dwordx4 v131, v[40:43], s[4:5]
	s_add_u32 s4, s4, 0xd000
	s_addc_u32 s5, s5, 0
	s_waitcnt lgkmcnt(4)
	global_store_dwordx4 v131, v[44:47], s[4:5]
	s_add_u32 s4, s4, 0xd000
	s_addc_u32 s5, s5, 0
	s_waitcnt lgkmcnt(3)
	global_store_dwordx4 v131, v[48:51], s[4:5]
	s_add_u32 s4, s4, 0xd000
	s_addc_u32 s5, s5, 0
	s_waitcnt lgkmcnt(2)
	global_store_dwordx4 v131, v[52:55], s[4:5]
	s_add_u32 s4, s4, 0xd000
	s_addc_u32 s5, s5, 0
	s_waitcnt lgkmcnt(1)
	global_store_dwordx4 v131, v[56:59], s[4:5]
	s_add_u32 s4, s4, 0xd000
	s_addc_u32 s5, s5, 0
	s_waitcnt lgkmcnt(0)
	global_store_dwordx4 v131, v[60:63], s[4:5]
	s_add_i32 s26, s26, s68
	s_cmpk_gt_i32 s26, 0x3ff
	s_cbranch_scc0 .LBB0_163

; template <int NTW>
; DI void inproj_tile(const Params& p, int l, int mt, int ntile, char* lds) {
;     ...
; #pragma unroll 4
;   for (int i = 0; i < NCOLS / 16; ++i) {
;     const int c = tid + 256 * i, tl = c / (NCOLS / 8), ch = c % (NCOLS / 8);
;     const u32x4 v = *(const u32x4*)(lds + tl * RS + ch * 16);
;     *(u32x4*)(proj + ((size_t)mt * 128 + tl) * NP + ntile * NCOLS + ch * 8) = v;
;   }
.LBB0_220:
	v_lshrrev_b32_e32 v128, 5, v181
	v_and_b32_e32 v129, 31, v181
	v_lshlrev_b32_e32 v129, 4, v129
	v_mad_u32_u24 v130, v128, s73, v129
	v_mad_u32_u24 v131, v128, s33, v129
	s_mul_i32 s4, s80, s33
	s_add_u32 s4, s0, s4
	s_addc_u32 s5, s1, 0
	ds_read_b128 v[0:3], v130
	ds_read_b128 v[4:7], v130 offset:4224
	ds_read_b128 v[8:11], v130 offset:8448
	ds_read_b128 v[12:15], v130 offset:12672
	ds_read_b128 v[16:19], v130 offset:16896
	ds_read_b128 v[20:23], v130 offset:21120
	ds_read_b128 v[24:27], v130 offset:25344
	ds_read_b128 v[28:31], v130 offset:29568
	ds_read_b128 v[32:35], v130 offset:33792
	ds_read_b128 v[36:39], v130 offset:38016
	ds_read_b128 v[40:43], v130 offset:42240
	ds_read_b128 v[44:47], v130 offset:46464
	ds_read_b128 v[48:51], v130 offset:50688
	ds_read_b128 v[52:55], v130 offset:54912
	ds_read_b128 v[56:59], v130 offset:59136
	ds_read_b128 v[60:63], v130 offset:63360
	s_waitcnt lgkmcnt(15)
	global_store_dwordx4 v131, v[0:3], s[4:5]
	s_add_u32 s4, s4, 0xd000
	s_addc_u32 s5, s5, 0
	s_waitcnt lgkmcnt(14)
	global_store_dwordx4 v131, v[4:7], s[4:5]
	s_add_u32 s4, s4, 0xd000
	s_addc_u32 s5, s5, 0
	s_waitcnt lgkmcnt(13)
	global_store_dwordx4 v131, v[8:11], s[4:5]
	s_add_u32 s4, s4, 0xd000
	s_addc_u32 s5, s5, 0
	s_waitcnt lgkmcnt(12)
	global_store_dwordx4 v131, v[12:15], s[4:5]
	s_add_u32 s4, s4, 0xd000
	s_addc_u32 s5, s5, 0
	s_waitcnt lgkmcnt(11)
	global_store_dwordx4 v131, v[16:19], s[4:5]
	s_add_u32 s4, s4, 0xd000
	s_addc_u32 s5, s5, 0
	s_waitcnt lgkmcnt(10)
	global_store_dwordx4 v131, v[20:23], s[4:5]
	s_add_u32 s4, s4, 0xd000
	s_addc_u32 s5, s5, 0
	s_waitcnt lgkmcnt(9)
	global_store_dwordx4 v131, v[24:27], s[4:5]
	s_add_u32 s4, s4, 0xd000
	s_addc_u32 s5, s5, 0
	s_waitcnt lgkmcnt(8)
	global_store_dwordx4 v131, v[28:31], s[4:5]
	s_add_u32 s4, s4, 0xd000
	s_addc_u32 s5, s5, 0
	s_waitcnt lgkmcnt(7)
	global_store_dwordx4 v131, v[32:35], s[4:5]
	s_add_u32 s4, s4, 0xd000
	s_addc_u32 s5, s5, 0
	s_waitcnt lgkmcnt(6)
	global_store_dwordx4 v131, v[36:39], s[4:5]
	s_add_u32 s4, s4, 0xd000
	s_addc_u32 s5, s5, 0
	s_waitcnt lgkmcnt(5)
	global_store_dwordx4 v131, v[40:43], s[4:5]
	s_add_u32 s4, s4, 0xd000
	s_addc_u32 s5, s5, 0
	s_waitcnt lgkmcnt(4)
	global_store_dwordx4 v131, v[44:47], s[4:5]
	s_add_u32 s4, s4, 0xd000
	s_addc_u32 s5, s5, 0
	s_waitcnt lgkmcnt(3)
	global_store_dwordx4 v131, v[48:51], s[4:5]
	s_add_u32 s4, s4, 0xd000
	s_addc_u32 s5, s5, 0
	s_waitcnt lgkmcnt(2)
	global_store_dwordx4 v131, v[52:55], s[4:5]
	s_add_u32 s4, s4, 0xd000
	s_addc_u32 s5, s5, 0
	s_waitcnt lgkmcnt(1)
	global_store_dwordx4 v131, v[56:59], s[4:5]
	s_add_u32 s4, s4, 0xd000
	s_addc_u32 s5, s5, 0
	s_waitcnt lgkmcnt(0)
	global_store_dwordx4 v131, v[60:63], s[4:5]
	s_cmp_eq_u32 s98, 2
	s_cbranch_scc1 .Lb_tile_late_done
